# attention: static s_setprio 1 for waves 4..7 (the two waves of a SIMD otherwise run each K/V step in lockstep)
# speedup vs baseline: 1.0383x; 1.0012x over previous
.LBB0_253:
	s_cmp_lt_i32 s28, 3
	s_cselect_b64 s[4:5], -1, 0
	s_and_b64 s[6:7], s[4:5], s[0:1]
	v_mov_b32_e32 v197, v196
	s_andn2_b64 vcc, exec, s[6:7]
	s_cbranch_vccnz .LBB0_343
	v_readfirstlane_b32 s0, v196
	s_cmpk_lt_u32 s0, 0x100
	s_cbranch_scc1 .Lap_skip
	s_setprio 1
.Lap_skip:
	s_ashr_i32 s1, s2, 31
	s_ashr_i32 s0, s30, 31
	s_lshr_b32 s1, s1, 29
	s_lshr_b32 s0, s0, 29
	s_add_i32 s1, s2, s1
	s_add_i32 s0, s30, s0
	s_and_b32 s3, s1, -8
	s_ashr_i32 s0, s0, 3
	s_sub_i32 s3, s2, s3
	s_mul_i32 s0, s0, s3
	s_ashr_i32 s1, s1, 3
	s_add_i32 s0, s0, s1
	s_and_b32 s3, s0, 3
	s_waitcnt lgkmcnt(0)
	s_xor_b32 s52, s3, 7
	s_ashr_i32 s4, s0, 2
	s_cmp_lg_u32 0, -1
	s_cselect_b32 s0, 0, 0
	s_ashr_i32 s5, s4, 31
	s_lshr_b32 s8, s5, 29
	s_add_i32 s8, s4, s8
	s_ashr_i32 s10, s8, 3
	s_and_b32 s8, s8, 0x3fffff8
	s_sub_i32 s8, s4, s8
	v_lshlrev_b32_e32 v4, 1, v196
	s_lshl_b32 s14, s8, 6
	v_and_b32_e32 v4, 32, v4
	s_addk_i32 s0, 0x6000
	s_ashr_i32 s11, s10, 31
	s_ashr_i32 s15, s14, 31
	v_add_u32_e32 v5, s0, v4
	s_add_i32 s0, 0, 0x15000
	s_lshl_b64 s[12:13], s[10:11], 11
	s_lshl_b64 s[4:5], s[4:5], 13
	s_lshl_b64 s[18:19], s[14:15], 1
	s_lshl_b64 s[10:11], s[10:11], 21
	s_add_u32 s8, s70, s10
	s_addc_u32 s11, s71, s11
	s_add_u32 s10, s8, s18
	s_addc_u32 s11, s11, s19
	v_and_b32_e32 v217, 31, v196
	v_lshrrev_b32_e32 v0, 5, v139
	s_add_u32 s14, s10, 0x6000000
	v_lshlrev_b32_e32 v221, 2, v0
	v_lshrrev_b32_e32 v6, 2, v196
	v_lshlrev_b32_e32 v7, 10, v0
	v_lshlrev_b32_e32 v8, 4, v217
	s_addc_u32 s15, s11, 0
	v_lshlrev_b32_e32 v3, 3, v196
	v_and_or_b32 v6, v6, 3, v221
	v_add3_u32 v222, 0, v7, v8
	v_lshlrev_b32_e32 v7, 4, v0
	v_lshlrev_b32_e32 v227, 9, v0
	v_lshrrev_b32_e32 v0, 3, v139
	s_add_u32 s4, s70, s4
	v_and_b32_e32 v2, 24, v3
	v_lshlrev_b32_e32 v6, 6, v6
	v_add_u32_e32 v4, 0, v4
	v_and_b32_e32 v228, 56, v3
	v_or_b32_e32 v3, 8, v0
	s_addc_u32 s5, s71, s5
	v_add3_u32 v223, v4, v2, v6
	v_add3_u32 v225, v5, v2, v6
	v_lshlrev_b32_e32 v229, 7, v0
	v_lshlrev_b32_e32 v4, 10, v0
	v_lshlrev_b32_e32 v230, 7, v3
	v_lshlrev_b32_e32 v6, 10, v3
	v_or_b32_e32 v3, 16, v0
	v_or_b32_e32 v0, 24, v0
	s_add_u32 s16, s4, 0x1980000
	v_mov_b32_e32 v1, 0
	v_lshlrev_b32_e32 v232, 7, v0
	v_lshlrev_b32_e32 v10, 10, v0
	v_lshlrev_b32_e32 v0, 10, v139
	s_addc_u32 s17, s5, 0
	v_lshl_add_u64 v[12:13], s[10:11], 0, v[0:1]
	v_lshlrev_b32_e32 v0, 4, v139
	s_add_u32 s4, s70, s18
	s_mov_b64 s[10:11], 0x5000000
	v_lshl_add_u64 v[200:201], s[16:17], 0, v[0:1]
	v_lshl_or_b32 v0, v217, 10, v7
	s_addc_u32 s5, s71, s19
	v_lshl_add_u64 v[198:199], v[12:13], 0, s[10:11]
	v_lshl_add_u64 v[12:13], s[4:5], 0, v[0:1]
	s_mov_b64 s[10:11], 0x4000000
	v_lshlrev_b32_e32 v0, 1, v228
	v_lshlrev_b32_e32 v8, 10, v3
	v_lshl_add_u64 v[202:203], v[12:13], 0, s[10:11]
	v_lshl_add_u64 v[12:13], s[4:5], 0, v[0:1]
	s_mov_b64 s[4:5], 0x9000000
	v_add_u32_e32 v0, 0, v7
	s_mov_b32 s38, 0xffff0000
	v_lshrrev_b32_e32 v220, 2, v139
	s_mov_b32 s9, 0
	v_add_u32_e32 v224, s0, v7
	v_cmp_gt_u32_e64 s[0:1], 32, v139
	v_or_b32_e32 v226, 0xc0, v221
	v_lshlrev_b32_e32 v231, 7, v3
	v_or_b32_e32 v254, 18, v221
	v_or_b32_e32 v233, 50, v221
	v_or_b32_e32 v242, 24, v221
	v_or_b32_e32 v243, 56, v221
	v_or_b32_e32 v244, 25, v221
	v_or_b32_e32 v245, 57, v221
	v_or_b32_e32 v246, 26, v221
	v_or_b32_e32 v247, 58, v221
	v_or_b32_e32 v248, 27, v221
	v_or_b32_e32 v249, 59, v221
	v_lshl_add_u64 v[204:205], v[12:13], 0, s[4:5]
	v_add_u32_e32 v250, 0x15100, v0
	v_or_b32_e32 v251, 0x7b, v221
	s_mov_b64 s[4:5], -1
	v_lshlrev_b32_e32 v206, 1, v2
	s_mov_b64 s[18:19], 0x10000
	s_mov_b64 s[20:21], 0x20000
	s_mov_b64 s[26:27], 0x30000
	s_mov_b64 s[36:37], 0x50000
	s_mov_b32 s39, -1
	s_mov_b32 s35, 0x42c00000
	s_mov_b64 s[40:41], 0x40000
	v_lshlrev_b32_e32 v208, 1, v4
	v_lshlrev_b32_e32 v210, 1, v6
	v_lshlrev_b32_e32 v212, 1, v8
	v_lshlrev_b32_e32 v214, 1, v10
	v_mov_b32_e32 v252, 0xff800000
	s_branch .LBB0_256

.LBB0_334:
	s_setprio 0
	s_cmpk_gt_i32 s2, 0xff
	s_cbranch_scc1 .LBB0_343
	v_mbcnt_lo_u32_b32 v6, -1, 0
	v_mbcnt_hi_u32_b32 v6, -1, v6
	v_and_b32_e32 v8, 64, v6
	v_lshlrev_b32_e32 v1, 2, v197
	v_xor_b32_e32 v7, 32, v6
	v_add_u32_e32 v8, 64, v8
	v_and_b32_e32 v3, 16, v1
	v_lshrrev_b32_e32 v1, 1, v197
	s_add_u32 s4, s70, 0x1a00000
	s_mov_b32 s35, 0
	v_cmp_lt_i32_e32 vcc, v7, v8
	v_and_b32_e32 v0, 63, v197
	s_addc_u32 s5, s71, 0
	v_cndmask_b32_e32 v6, v6, v7, vcc
	s_lshl_b64 s[8:9], s[34:35], 7
	v_and_b32_e32 v7, 16, v1
	v_and_b32_e32 v2, 31, v197
	v_and_b32_e32 v4, 12, v1
	v_cmp_gt_u32_e64 s[0:1], 32, v0
	v_lshlrev_b32_e32 v114, 3, v0
	v_or_b32_e32 v0, s8, v7
	v_mov_b32_e32 v1, s9
	s_mov_b64 s[8:9], 0x7000000
	v_lshl_add_u64 v[116:117], v[0:1], 0, s[8:9]
	s_lshl_b64 s[8:9], s[34:35], 14
	v_lshlrev_b32_e32 v0, 5, v2
	v_and_b32_e32 v5, 3, v197
	v_lshlrev_b32_e32 v113, 2, v6
	v_lshlrev_b32_e32 v6, 1, v2
	v_or3_b32 v0, s8, v0, v7
	v_mov_b32_e32 v1, s9
	s_mov_b64 s[8:9], 0x1a80800
	v_or3_b32 v112, v4, v5, v3
	s_lshl_b32 s3, s34, 2
	v_or3_b32 v118, v3, v4, v5
	v_lshl_or_b32 v115, s34, 9, v6
	v_lshl_add_u64 v[120:121], v[0:1], 0, s[8:9]
	s_mov_b64 s[8:9], 0x8000
	v_mov_b32_e32 v122, 2.0
	s_mov_b64 s[12:13], 0x200
	s_mov_b64 s[14:15], 0x1000
	s_and_b32 s10, s2, 7
	s_lshl_b32 s10, s10, 5
	s_lshr_b32 s11, s2, 3
	s_add_i32 s10, s10, s11
	s_mov_b32 s11, s10
	s_branch .LBB0_337
